# raised wave priority (s_setprio 2) while a block runs the weight-conversion hook beside the co-resident attention block
# baseline (speedup 1.0000x reference)
; __device__ __forceinline__ u16 f2bf(float f) { return (u16)(pack2(f, 0.f) & 0xffffu); }
; __device__ __forceinline__ int tid_() { int t = threadIdx.x; asm volatile("" : "+v"(t)); return t; }
; __device__ __forceinline__ void convT_tile(const float* __restrict__ src, int lds, int k0, int c0, u16* __restrict__ dst, int Kd,
;                                            int rbase, int mode, int which, unsigned char* smem, const float* __restrict__ kscale = nullptr) {
;   float* tile = (float*)smem;
;   const int t = tid_();
;   float4 v4[4];
; #pragma unroll
;   for (int i = 0; i < 4; ++i) {
;     const f32x4 w_ = __builtin_nontemporal_load((const f32x4*)(src + (size_t)(k0 + i * 16 + (t >> 4)) * lds + c0 + (t & 15) * 4));
;     v4[i] = make_float4(w_[0], w_[1], w_[2], w_[3]);
;   }
; #pragma unroll
;   for (int i = 0; i < 4; ++i) {
;     const int kk = i * 16 + (t >> 4), cc = (t & 15) * 4;
;     const float sc = kscale ? kscale[k0 + kk] : 1.f;
;     tile[kk * 65 + cc + 0] = v4[i].x * sc; tile[kk * 65 + cc + 1] = v4[i].y * sc;
;     tile[kk * 65 + cc + 2] = v4[i].z * sc; tile[kk * 65 + cc + 3] = v4[i].w * sc;
;   }
;   __syncthreads();
; #pragma unroll
;   for (int i = 0; i < 16; ++i) {
;     const int cc = i * 4 + (t >> 6), kk = t & 63;
;     int row;
;     if (mode == 0) row = rbase + cc;
;     else { const int f = c0 + cc; row = (((f >> 4) * 2 + which) << 4) + (f & 15); }
;     dst[(size_t)row * Kd + k0 + kk] = f2bf(tile[kk * 65 + cc]);
;   }
;   __syncthreads();
; }
; __device__ __forceinline__ void conv_item(const Params& p, int it, unsigned char* smem) {
;     ...
;   if (r < 4096) {
;     const int which = r >> 11, r2 = r & 2047, e = r2 >> 7, r3 = r2 & 127, ct = r3 >> 4, kt = r3 & 15;
;     const float* src = (which ? p.w_up : p.w_gate) + (size_t)(l * 16 + e) * 1024 * 512;
;     convT_tile(src, 512, kt * 64, ct * 64, p.WguT + (size_t)(l * 16 + e) * 1024 * 1024, 1024, 0, 1, which, smem);
;     return;
.Lcv_entry:
	s_setprio 2
	s_load_dwordx2 s[52:53], s[4:5], 0x90
	s_load_dwordx2 s[54:55], s[4:5], 0x98
	s_load_dwordx2 s[56:57], s[4:5], 0xa0
	s_load_dwordx2 s[98:99], s[4:5], 0xe0
	s_load_dwordx2 s[100:101], s[4:5], 0xe8
	v_lshrrev_b32_e32 v98, 4, v187
	v_add_u32_e32 v99, 16, v98
	v_add_u32_e32 v100, 32, v98
	v_add_u32_e32 v101, 48, v98
	v_and_b32_e32 v122, 15, v187
	v_lshlrev_b32_e32 v102, 4, v122
	v_lshrrev_b32_e32 v123, 3, v187
	v_and_b32_e32 v122, 7, v187
	v_lshrrev_b32_e32 v36, 4, v123
	v_and_b32_e32 v37, 15, v123
	v_lshl_add_u32 v36, v36, 5, v37
	v_lshlrev_b32_e32 v36, 11, v36
	v_lshl_add_u32 v103, v122, 4, v36
	v_lshlrev_b32_e32 v36, 10, v123
	v_lshl_add_u32 v105, v122, 4, v36
	v_add_u32_e32 v123, 32, v123
	v_lshrrev_b32_e32 v36, 4, v123
	v_and_b32_e32 v37, 15, v123
	v_lshl_add_u32 v36, v36, 5, v37
	v_lshlrev_b32_e32 v36, 11, v36
	v_lshl_add_u32 v104, v122, 4, v36
	v_lshlrev_b32_e32 v36, 10, v123
	v_lshl_add_u32 v106, v122, 4, v36
	v_subrev_u32_e32 v123, 32, v123
	v_mul_u32_u24_e32 v36, 0x820, v122
	v_lshl_add_u32 v115, v123, 2, v36
	v_mul_u32_u24_e32 v37, 0x104, v98
	v_add_u32_e32 v107, v37, v102
	v_add_u32_e32 v111, 0x4100, v107
	v_mul_u32_u24_e32 v37, 0x104, v99
	v_add_u32_e32 v108, v37, v102
	v_add_u32_e32 v112, 0x4100, v108
	v_mul_u32_u24_e32 v37, 0x104, v100
	v_add_u32_e32 v109, v37, v102
	v_add_u32_e32 v113, 0x4100, v109
	v_mul_u32_u24_e32 v37, 0x104, v101
	v_add_u32_e32 v110, v37, v102
	v_add_u32_e32 v114, 0x4100, v110
	s_mov_b32 s34, -1
	s_cmp_lg_u32 s36, 0
	s_cbranch_scc1 .Lcv_noex
	s_cmp_lt_u32 s2, 16
	s_cbranch_scc1 .Lcv_exit
	s_cmp_lt_u32 s2, 208
	s_cbranch_scc0 .Lcv_noex
	s_sub_i32 s0, s2, 16
	s_and_b32 s34, s0, 15
	s_lshr_b32 s0, s0, 4
	s_lshl_b32 s0, s0, 9
	s_add_i32 s34, s34, s0

; __device__ __forceinline__ void convT_tile(const float* __restrict__ src, int lds, int k0, int c0, u16* __restrict__ dst, int Kd,
;                                            int rbase, int mode, int which, unsigned char* smem, const float* __restrict__ kscale = nullptr) {
;     ...
;   }
;   __syncthreads();
; }
.Lcv_exit:
	s_waitcnt vmcnt(0) lgkmcnt(0)
	s_barrier
	s_setprio 0
	s_cmp_eq_u32 s32, 0
	s_cbranch_scc1 .Lcv_ret_pre
	s_branch .Lcv_ret_post
